# adds phase0 W_in transpose: the 8 guarded row loads of a tile issued together, one wait
# speedup vs baseline: 1.0485x; 1.0079x over previous
.LBB0_38:
	s_andn2_b64 vcc, exec, s[6:7]
	s_cbranch_vccnz .LBB0_28
	s_waitcnt lgkmcnt(0)
	s_ashr_i32 s0, s19, 31
	s_lshr_b32 s0, s0, 28
	s_add_i32 s0, s19, s0
	s_and_b32 s6, s0, 0x3fffff0
	s_lshl_b32 s0, s0, 2
	v_mbcnt_lo_u32_b32 v0, -1, 0
	v_mbcnt_hi_u32_b32 v0, -1, v0
	v_readlane_b32 s52, v254, 2
	v_add_u32_e32 v2, s1, v0
	v_ashrrev_i32_e32 v5, 6, v2
	v_bfi_b32 v2, 63, v0, s0
	s_sub_i32 s6, s19, s6
	v_ashrrev_i32_e32 v3, 31, v2
	v_readlane_b32 s53, v254, 3
	s_lshl_b32 s6, s6, 6
	v_cmp_gt_i32_e32 vcc, s17, v2
	v_lshl_add_u64 v[2:3], v[2:3], 2, s[52:53]
	v_mov_b32_e32 v7, 0
	v_mov_b32_e32 v6, 0
	v_readlane_b32 s54, v254, 4
	v_readlane_b32 s55, v254, 5
	v_readlane_b32 s56, v254, 6
	v_readlane_b32 s57, v254, 7
	v_readlane_b32 s58, v254, 8
	v_readlane_b32 s59, v254, 9
	v_readlane_b32 s60, v254, 10
	v_readlane_b32 s61, v254, 11
	v_readlane_b32 s62, v254, 12
	v_readlane_b32 s63, v254, 13
	v_readlane_b32 s64, v254, 14
	v_readlane_b32 s65, v254, 15
	v_readlane_b32 s66, v254, 16
	v_readlane_b32 s67, v254, 17
	v_mov_b32_e32 v20, 0
	v_mov_b32_e32 v21, 0
	v_mov_b32_e32 v22, 0
	v_mov_b32_e32 v23, 0
	v_mov_b32_e32 v24, 0
	v_mov_b32_e32 v25, 0
	v_mov_b32_e32 v26, 0
	v_mov_b32_e32 v27, 0
	s_and_saveexec_b64 s[8:9], vcc
	s_cbranch_execz .Ltr_ld_done
	v_add_u32_e32 v28, s6, v5
	v_mad_i64_i32 v[30:31], s[20:21], v28, s18, v[2:3]
	global_load_dword v20, v[30:31], off
	v_add_u32_e32 v28, 8, v5
	v_add_u32_e32 v28, s6, v28
	v_mad_i64_i32 v[30:31], s[20:21], v28, s18, v[2:3]
	global_load_dword v21, v[30:31], off
	v_add_u32_e32 v28, 16, v5
	v_add_u32_e32 v28, s6, v28
	v_mad_i64_i32 v[30:31], s[20:21], v28, s18, v[2:3]
	global_load_dword v22, v[30:31], off
	v_add_u32_e32 v28, 24, v5
	v_add_u32_e32 v28, s6, v28
	v_mad_i64_i32 v[30:31], s[20:21], v28, s18, v[2:3]
	global_load_dword v23, v[30:31], off
	v_add_u32_e32 v28, 32, v5
	v_add_u32_e32 v28, s6, v28
	v_mad_i64_i32 v[30:31], s[20:21], v28, s18, v[2:3]
	global_load_dword v24, v[30:31], off
	v_add_u32_e32 v28, 40, v5
	v_add_u32_e32 v28, s6, v28
	v_mad_i64_i32 v[30:31], s[20:21], v28, s18, v[2:3]
	global_load_dword v25, v[30:31], off
	v_add_u32_e32 v28, 48, v5
	v_add_u32_e32 v28, s6, v28
	v_mad_i64_i32 v[30:31], s[20:21], v28, s18, v[2:3]
	global_load_dword v26, v[30:31], off
	v_add_u32_e32 v28, 56, v5
	v_add_u32_e32 v28, s6, v28
	v_mad_i64_i32 v[30:31], s[20:21], v28, s18, v[2:3]
	global_load_dword v27, v[30:31], off
.Ltr_ld_done:
	s_or_b64 exec, exec, s[8:9]
	v_and_b32_e32 v0, 63, v0
	v_lshlrev_b32_e32 v8, 2, v0
	v_mul_lo_u32 v9, v5, s16
	v_add_u32_e32 v12, v8, v9
	s_waitcnt vmcnt(0)
	ds_write_b32 v12, v20
	ds_write_b32 v12, v21 offset:2080
	ds_write_b32 v12, v22 offset:4160
	ds_write_b32 v12, v23 offset:6240
	ds_write_b32 v12, v24 offset:8320
	ds_write_b32 v12, v25 offset:10400
	ds_write_b32 v12, v26 offset:12480
	v_add_u32_e32 v6, 8, v5
	v_add_u32_e32 v7, 16, v5
	v_add_u32_e32 v8, 24, v5
	v_add_u32_e32 v9, 32, v5
	v_add_u32_e32 v10, 40, v5
	v_add_u32_e32 v11, 48, v5
	v_add_u32_e32 v13, 56, v5
	v_mov_b32_e32 v14, v27
	s_branch .LBB0_27
